# hand-written residual epilogue for the bf16-residual fused-norm phases: 14 residual loads in flight, XB stores issued after the row-stat publish so they drain during the panel exchange
# baseline (speedup 1.0000x reference)
;     __device__ __forceinline__ void operator()(const f32x4 (&acc)[2][2][4][2], const Unit& u, int wr, int wc, int fr_in, int fq_in) const {
;         int tt = threadIdx.x; asm volatile("" : "+v"(tt)); const int fr = tt & 15, fq = (tt >> 4) & 3; (void)fr_in; (void)fq_in;
;         const size_t off0 = (size_t)(wr * 64 + fr) * u.ldc + wc * 32 + 8 * fq;
;         bf16_t* O = (bf16_t*)u.O; const bool r32 = (u.flag & 1) != 0;
;         const float* R32 = u.R; const bf16_t* R16 = (const bf16_t*)u.R;
; #pragma unroll
;         for (int ai = 0; ai < 2; ++ai)
; #pragma unroll
;             for (int mh = 0; mh < 2; ++mh) {
;                 f32x4 rv[2][2][2];
;                 if (r32) {
; #pragma unroll
;                     for (int m2 = 0; m2 < 2; ++m2)
; #pragma unroll
;                         for (int bj = 0; bj < 2; ++bj)
; #pragma unroll
;                             for (int n = 0; n < 2; ++n) rv[m2][bj][n] = *(const f32x4*)(R32 + off0 + (size_t)(ai * HALF + (2 * mh + m2) * 16) * u.ldc + bj * HALF + 4 * n);
.LBB0_321:
	v_mov_b32_e32 v128, v185
	v_readlane_b32 s0, v254, 48
	s_ashr_i32 s13, s12, 31
	s_mov_b64 s[56:57], -1
	v_and_or_b32 v129, v128, 15, s0
	v_lshrrev_b32_e32 v128, 1, v128
	v_and_or_b32 v182, v128, 24, s80
	v_and_b32_e32 v128, 1, v180
	v_mad_i64_i32 v[174:175], s[0:1], v129, s12, v[182:183]
	v_cmp_eq_u32_e32 vcc, 0, v128
	v_cmp_eq_u32_e64 s[0:1], 1, v128
	v_lshl_add_u64 v[178:179], v[174:175], 2, s[40:41]
	s_and_b64 vcc, exec, vcc
	s_branch .Lep_begin
.Lep_ret:
	s_lshl_b64 s[38:39], s[12:13], 6
	v_lshl_add_u64 v[140:141], v[178:179], 0, s[38:39]
	global_load_dwordx4 v[144:147], v[178:179], off offset:16
	global_load_dwordx4 v[128:131], v[178:179], off
	global_load_dwordx4 v[148:151], v[178:179], off offset:528
	global_load_dwordx4 v[132:135], v[178:179], off offset:512
	global_load_dwordx4 v[152:155], v[140:141], off offset:16
	global_load_dwordx4 v[136:139], v[140:141], off
	global_load_dwordx4 v[156:159], v[140:141], off offset:528
	s_nop 0
	global_load_dwordx4 v[140:143], v[140:141], off offset:512
	s_lshl_b64 s[38:39], s[12:13], 5
	s_mov_b64 s[56:57], 0

; __device__ __forceinline__ float bflo(unsigned w) { return __uint_as_float(w << 16); }
; __device__ __forceinline__ float bfhi(unsigned w) { return __uint_as_float(w & 0xffff0000u); }
; __device__ __forceinline__ unsigned cvt_pk_bf16(float lo, float hi) { unsigned r; asm volatile("v_cvt_pk_bf16_f32 %0, %1, %2" : "=v"(r) : "v"(lo), "v"(hi)); return r; }
;     __device__ __forceinline__ void operator()(const f32x4 (&acc)[2][2][4][2], const Unit& u, int wr, int wc, int fr_in, int fq_in) const {
;     ...
;                     u32x4 rb[2][2];
; #pragma unroll
;                     for (int m2 = 0; m2 < 2; ++m2)
; #pragma unroll
;                         for (int bj = 0; bj < 2; ++bj) rb[m2][bj] = *(const u32x4*)(R16 + off0 + (size_t)(ai * HALF + (2 * mh + m2) * 16) * u.ldc + bj * HALF);
; #pragma unroll
;                     for (int m2 = 0; m2 < 2; ++m2)
; #pragma unroll
;                         for (int bj = 0; bj < 2; ++bj) { const u32x4 t = rb[m2][bj]; rv[m2][bj][0] = (f32x4){bflo(t.x), bfhi(t.x), bflo(t.y), bfhi(t.y)}; rv[m2][bj][1] = (f32x4){bflo(t.z), bfhi(t.z), bflo(t.w), bfhi(t.w)}; }
;                 }
;                 asm volatile("" ::: "memory");
; #pragma unroll
;                 for (int m2 = 0; m2 < 2; ++m2) { const int m = 2 * mh + m2; const size_t off = off0 + (size_t)(ai * HALF + m * 16) * u.ldc;
; #pragma unroll
;                     for (int bj = 0; bj < 2; ++bj) { const f32x4 v0 = acc[ai][bj][m][0] + rv[m2][bj][0], v1 = acc[ai][bj][m][1] + rv[m2][bj][1];
;                         u32x4 w; w.x = cvt_pk_bf16(v0[0], v0[1]); w.y = cvt_pk_bf16(v0[2], v0[3]); w.z = cvt_pk_bf16(v1[0], v1[1]); w.w = cvt_pk_bf16(v1[2], v1[3]);
; template <bool OUT_F32, bool IN_BF16>
; __device__ __forceinline__ void phase_rmsnorm(const void* Xv, const float* gain, void* out) {
;     ...
;         for (int r = 0; r < RPT; ++r) { float sq = 0.f;
; #pragma unroll
;             for (int j = 0; j < 4; ++j) { if (IN_BF16) { const u32x4 q = t[r][j]; v[r][j][0] = (f32x4){bflo(q.x), bfhi(q.x), bflo(q.y), bfhi(q.y)}; v[r][j][1] = (f32x4){bflo(q.z), bfhi(q.z), bflo(q.w), bfhi(q.w)}; }
; #pragma unroll
;                 for (int h = 0; h < 2; ++h) { const f32x4 a = v[r][j][h]; sq += (a.x * a.x + a.y * a.y) + (a.z * a.z + a.w * a.w); } }
;             rs[r] = 1.0f / sqrtf(wave_sum(sq) * (1.0f / DM) + EPS); }
.Lep_begin:
	s_cbranch_vccz .Lep_old
	s_and_b32 s38, s90, 7
	s_cmp_eq_u32 s38, 5
	s_cbranch_scc1 .Lep_k4
	s_cmp_lg_u32 s38, 0
	s_cbranch_scc1 .Lep_old
	s_cmp_eq_u32 s90, 32
	s_cbranch_scc1 .Lep_old
	s_andn2_b64 vcc, exec, s[64:65]
	s_mov_b64 s[100:101], vcc
	s_lshr_b32 s1, s90, 3
	s_lshl_b32 s13, s1, 13
	s_lshl_b32 s1, s1, 1
	s_add_i32 s1, s1, -1
	s_mov_b32 s0, 0
	s_branch .Lep_go
.Lep_old:
	s_cbranch_vccnz .LBB0_323
	s_branch .Lep_ret
.Lep_k4:
	s_cmp_eq_u32 s90, 5
	s_cbranch_scc1 .Lep_old
	s_andn2_b64 vcc, exec, s[64:65]
	s_mov_b64 s[100:101], vcc
	s_add_i32 s1, s90, -5
	s_lshr_b32 s1, s1, 3
	s_lshl_b32 s13, s1, 13
	s_lshl_b32 s1, s1, 1
	s_mov_b32 s0, 1
.Lep_go:
	v_lshl_add_u64 v[176:177], v[174:175], 1, s[40:41]
	v_lshl_add_u64 v[174:175], v[174:175], 1, s[8:9]
	s_mov_b32 s64, 0x10000
	s_mov_b32 s65, 0
	global_load_dwordx4 v[128:131], v[176:177], off
	global_load_dwordx4 v[132:135], v[176:177], off offset:256
	v_lshl_add_u64 v[176:177], v[176:177], 0, s[64:65]
	global_load_dwordx4 v[136:139], v[176:177], off
	global_load_dwordx4 v[140:143], v[176:177], off offset:256
	v_lshl_add_u64 v[176:177], v[176:177], 0, s[64:65]
	global_load_dwordx4 v[144:147], v[176:177], off
	global_load_dwordx4 v[148:151], v[176:177], off offset:256
	v_lshl_add_u64 v[176:177], v[176:177], 0, s[64:65]
	global_load_dwordx4 v[152:155], v[176:177], off
	global_load_dwordx4 v[156:159], v[176:177], off offset:256
	s_mov_b32 s64, 0x50000
	v_lshl_add_u64 v[176:177], v[176:177], 0, s[64:65]
	s_mov_b32 s64, 0x10000
	global_load_dwordx4 v[192:195], v[176:177], off
	global_load_dwordx4 v[196:199], v[176:177], off offset:256
	v_lshl_add_u64 v[176:177], v[176:177], 0, s[64:65]
	global_load_dwordx4 v[200:203], v[176:177], off
	global_load_dwordx4 v[224:227], v[176:177], off offset:256
	v_lshl_add_u64 v[176:177], v[176:177], 0, s[64:65]
	global_load_dwordx4 v[228:231], v[176:177], off
	global_load_dwordx4 v[232:235], v[176:177], off offset:256
	v_lshl_add_u64 v[176:177], v[176:177], 0, s[64:65]
	v_readlane_b32 s38, v252, 2
	v_readlane_b32 s39, v252, 3
	s_nop 0
	s_sub_u32 s38, s38, 0x90
	s_subb_u32 s39, s39, 0
	s_load_dwordx4 s[56:59], s[38:39], 0x38
	s_waitcnt lgkmcnt(0)
	s_cmp_eq_u32 s0, 1
	s_cselect_b32 s56, s58, s56
	s_cselect_b32 s57, s59, s57
	s_add_u32 s56, s56, s13
	s_addc_u32 s57, s57, 0
	v_readfirstlane_b32 s58, v174
	v_readfirstlane_b32 s59, v175
	s_add_u32 s64, s88, 0x1b900000
	s_addc_u32 s65, s89, 0
	s_sub_u32 s58, s58, s64
	s_subb_u32 s59, s59, s65
	s_lshr_b32 s13, s58, 20
	s_bfe_u32 s0, s58, 0x30009
	s_lshl_b32 s58, s1, 18
	s_lshl_b32 s59, s13, 13
	s_add_i32 s58, s58, s59
	s_add_u32 s38, s88, 0x30280000
	s_addc_u32 s39, s89, 0
	s_add_u32 s38, s38, s58
	s_addc_u32 s39, s39, 0
	s_lshl_b32 s1, s1, 5
	s_add_i32 s1, s1, s13
	s_lshl_b32 s1, s1, 6
	s_add_u32 s58, s88, 0x40a84000
	s_addc_u32 s59, s89, 0
	s_add_u32 s58, s58, s1
	s_addc_u32 s59, s59, 0
	s_lshl_b32 s1, s0, 10
	s_add_u32 s56, s56, s1
	s_addc_u32 s57, s57, 0
	v_mov_b32_e32 v244, 0
	v_mov_b32_e32 v245, 0
	v_mov_b32_e32 v246, 0
	v_mov_b32_e32 v247, 0
	v_mov_b32_e32 v248, 0
	v_mov_b32_e32 v249, 0
	v_mov_b32_e32 v250, 0
	v_mov_b32_e32 v251, 0
	s_waitcnt vmcnt(13)
	v_lshlrev_b32_e32 v236, 16, v128
	v_and_b32_e32 v237, 0xffff0000, v128
	v_lshlrev_b32_e32 v238, 16, v129
	v_and_b32_e32 v239, 0xffff0000, v129
	v_lshlrev_b32_e32 v240, 16, v130
	v_and_b32_e32 v241, 0xffff0000, v130
	v_lshlrev_b32_e32 v242, 16, v131
	v_and_b32_e32 v243, 0xffff0000, v131
	v_pk_add_f32 v[236:237], v[124:125], v[236:237]
	v_pk_add_f32 v[238:239], v[126:127], v[238:239]
	v_pk_add_f32 v[240:241], v[120:121], v[240:241]
	v_pk_add_f32 v[242:243], v[122:123], v[242:243]
	v_cvt_pk_bf16_f32 v124, v236, v237
	v_cvt_pk_bf16_f32 v125, v238, v239
	v_cvt_pk_bf16_f32 v126, v240, v241
	v_cvt_pk_bf16_f32 v127, v242, v243
	v_lshlrev_b32_e32 v236, 16, v124
	v_and_b32_e32 v237, 0xffff0000, v124
	v_lshlrev_b32_e32 v238, 16, v125
	v_and_b32_e32 v239, 0xffff0000, v125
	v_lshlrev_b32_e32 v240, 16, v126
	v_and_b32_e32 v241, 0xffff0000, v126
	v_lshlrev_b32_e32 v242, 16, v127
	v_and_b32_e32 v243, 0xffff0000, v127
	v_fmac_f32_e32 v244, v236, v236
	v_fmac_f32_e32 v244, v237, v237
	v_fmac_f32_e32 v244, v238, v238
	v_fmac_f32_e32 v244, v239, v239
	v_fmac_f32_e32 v244, v240, v240
	v_fmac_f32_e32 v244, v241, v241
	v_fmac_f32_e32 v244, v242, v242
	v_fmac_f32_e32 v244, v243, v243
	s_waitcnt vmcnt(12)
	v_lshlrev_b32_e32 v236, 16, v132
	v_and_b32_e32 v237, 0xffff0000, v132
	v_lshlrev_b32_e32 v238, 16, v133
	v_and_b32_e32 v239, 0xffff0000, v133
	v_lshlrev_b32_e32 v240, 16, v134
	v_and_b32_e32 v241, 0xffff0000, v134
	v_lshlrev_b32_e32 v242, 16, v135
	v_and_b32_e32 v243, 0xffff0000, v135
	v_pk_add_f32 v[236:237], v[92:93], v[236:237]
	v_pk_add_f32 v[238:239], v[94:95], v[238:239]
	v_pk_add_f32 v[240:241], v[88:89], v[240:241]
	v_pk_add_f32 v[242:243], v[90:91], v[242:243]
	v_cvt_pk_bf16_f32 v92, v236, v237
	v_cvt_pk_bf16_f32 v93, v238, v239
	v_cvt_pk_bf16_f32 v94, v240, v241
	v_cvt_pk_bf16_f32 v95, v242, v243
	global_load_dwordx4 v[128:131], v[176:177], off
	global_load_dwordx4 v[132:135], v[176:177], off offset:256
	v_lshlrev_b32_e32 v236, 16, v92
	v_and_b32_e32 v237, 0xffff0000, v92
	v_lshlrev_b32_e32 v238, 16, v93
	v_and_b32_e32 v239, 0xffff0000, v93
	v_lshlrev_b32_e32 v240, 16, v94
	v_and_b32_e32 v241, 0xffff0000, v94
	v_lshlrev_b32_e32 v242, 16, v95
	v_and_b32_e32 v243, 0xffff0000, v95
	v_fmac_f32_e32 v244, v236, v236
	v_fmac_f32_e32 v244, v237, v237
	v_fmac_f32_e32 v244, v238, v238
	v_fmac_f32_e32 v244, v239, v239
	v_fmac_f32_e32 v244, v240, v240
	v_fmac_f32_e32 v244, v241, v241
	v_fmac_f32_e32 v244, v242, v242
	v_fmac_f32_e32 v244, v243, v243
	s_waitcnt vmcnt(13)
; __device__ __forceinline__ float bflo(unsigned w) { return __uint_as_float(w << 16); }
; __device__ __forceinline__ float bfhi(unsigned w) { return __uint_as_float(w & 0xffff0000u); }
;     __device__ __forceinline__ void operator()(const f32x4 (&acc)[2][2][4][2], const Unit& u, int wr, int wc, int fr_in, int fq_in) const {
;     ...
;                         for (int bj = 0; bj < 2; ++bj) { const u32x4 t = rb[m2][bj]; rv[m2][bj][0] = (f32x4){bflo(t.x), bfhi(t.x), bflo(t.y), bfhi(t.y)}; rv[m2][bj][1] = (f32x4){bflo(t.z), bfhi(t.z), bflo(t.w), bfhi(t.w)}; }
;                 }
;                 asm volatile("" ::: "memory");
; #pragma unroll
;                 for (int m2 = 0; m2 < 2; ++m2) { const int m = 2 * mh + m2; const size_t off = off0 + (size_t)(ai * HALF + m * 16) * u.ldc;
; #pragma unroll
;                     for (int bj = 0; bj < 2; ++bj) { const f32x4 v0 = acc[ai][bj][m][0] + rv[m2][bj][0], v1 = acc[ai][bj][m][1] + rv[m2][bj][1];
; template <bool OUT_F32, bool IN_BF16>
; __device__ __forceinline__ void phase_rmsnorm(const void* Xv, const float* gain, void* out) {
;     ...
;         for (int r = 0; r < RPT; ++r) { float sq = 0.f;
; #pragma unroll
;             for (int j = 0; j < 4; ++j) { if (IN_BF16) { const u32x4 q = t[r][j]; v[r][j][0] = (f32x4){bflo(q.x), bfhi(q.x), bflo(q.y), bfhi(q.y)}; v[r][j][1] = (f32x4){bflo(q.z), bfhi(q.z), bflo(q.w), bfhi(q.w)}; }
; #pragma unroll
;                 for (int h = 0; h < 2; ++h) { const f32x4 a = v[r][j][h]; sq += (a.x * a.x + a.y * a.y) + (a.z * a.z + a.w * a.w); } }
	v_lshlrev_b32_e32 v236, 16, v136
	v_and_b32_e32 v237, 0xffff0000, v136
	v_lshlrev_b32_e32 v238, 16, v137
	v_and_b32_e32 v239, 0xffff0000, v137
	v_lshlrev_b32_e32 v240, 16, v138
	v_and_b32_e32 v241, 0xffff0000, v138
	v_lshlrev_b32_e32 v242, 16, v139
	v_and_b32_e32 v243, 0xffff0000, v139
	v_pk_add_f32 v[236:237], v[116:117], v[236:237]
	v_pk_add_f32 v[238:239], v[118:119], v[238:239]
	v_pk_add_f32 v[240:241], v[112:113], v[240:241]
	v_pk_add_f32 v[242:243], v[114:115], v[242:243]
	v_cvt_pk_bf16_f32 v116, v236, v237
	v_cvt_pk_bf16_f32 v117, v238, v239
	v_cvt_pk_bf16_f32 v118, v240, v241
	v_cvt_pk_bf16_f32 v119, v242, v243
	v_lshlrev_b32_e32 v236, 16, v116
	v_and_b32_e32 v237, 0xffff0000, v116
	v_lshlrev_b32_e32 v238, 16, v117
	v_and_b32_e32 v239, 0xffff0000, v117
	v_lshlrev_b32_e32 v240, 16, v118
	v_and_b32_e32 v241, 0xffff0000, v118
	v_lshlrev_b32_e32 v242, 16, v119
	v_and_b32_e32 v243, 0xffff0000, v119
	v_fmac_f32_e32 v245, v236, v236
	v_fmac_f32_e32 v245, v237, v237
	v_fmac_f32_e32 v245, v238, v238
	v_fmac_f32_e32 v245, v239, v239
	v_fmac_f32_e32 v245, v240, v240
	v_fmac_f32_e32 v245, v241, v241
	v_fmac_f32_e32 v245, v242, v242
	v_fmac_f32_e32 v245, v243, v243
	s_waitcnt vmcnt(12)
	v_lshlrev_b32_e32 v236, 16, v140
	v_and_b32_e32 v237, 0xffff0000, v140
	v_lshlrev_b32_e32 v238, 16, v141
	v_and_b32_e32 v239, 0xffff0000, v141
	v_lshlrev_b32_e32 v240, 16, v142
	v_and_b32_e32 v241, 0xffff0000, v142
	v_lshlrev_b32_e32 v242, 16, v143
	v_and_b32_e32 v243, 0xffff0000, v143
	v_pk_add_f32 v[236:237], v[84:85], v[236:237]
	v_pk_add_f32 v[238:239], v[86:87], v[238:239]
	v_pk_add_f32 v[240:241], v[80:81], v[240:241]
	v_pk_add_f32 v[242:243], v[82:83], v[242:243]
	v_cvt_pk_bf16_f32 v84, v236, v237
	v_cvt_pk_bf16_f32 v85, v238, v239
	v_cvt_pk_bf16_f32 v86, v240, v241
	v_cvt_pk_bf16_f32 v87, v242, v243
	v_lshlrev_b32_e32 v236, 16, v84
	v_and_b32_e32 v237, 0xffff0000, v84
	v_lshlrev_b32_e32 v238, 16, v85
	v_and_b32_e32 v239, 0xffff0000, v85
	v_lshlrev_b32_e32 v240, 16, v86
	v_and_b32_e32 v241, 0xffff0000, v86
	v_lshlrev_b32_e32 v242, 16, v87
	v_and_b32_e32 v243, 0xffff0000, v87
	v_fmac_f32_e32 v245, v236, v236
	v_fmac_f32_e32 v245, v237, v237
	v_fmac_f32_e32 v245, v238, v238
	v_fmac_f32_e32 v245, v239, v239
	v_fmac_f32_e32 v245, v240, v240
	v_fmac_f32_e32 v245, v241, v241
	v_fmac_f32_e32 v245, v242, v242
	v_fmac_f32_e32 v245, v243, v243
	s_waitcnt vmcnt(11)
	v_lshlrev_b32_e32 v236, 16, v144
	v_and_b32_e32 v237, 0xffff0000, v144
	v_lshlrev_b32_e32 v238, 16, v145
	v_and_b32_e32 v239, 0xffff0000, v145
	v_lshlrev_b32_e32 v240, 16, v146
	v_and_b32_e32 v241, 0xffff0000, v146
	v_lshlrev_b32_e32 v242, 16, v147
	v_and_b32_e32 v243, 0xffff0000, v147
	v_pk_add_f32 v[236:237], v[108:109], v[236:237]
	v_pk_add_f32 v[238:239], v[110:111], v[238:239]
	v_pk_add_f32 v[240:241], v[104:105], v[240:241]
	v_pk_add_f32 v[242:243], v[106:107], v[242:243]
	v_cvt_pk_bf16_f32 v108, v236, v237
	v_cvt_pk_bf16_f32 v109, v238, v239
	v_cvt_pk_bf16_f32 v110, v240, v241
	v_cvt_pk_bf16_f32 v111, v242, v243
	v_lshlrev_b32_e32 v236, 16, v108
	v_and_b32_e32 v237, 0xffff0000, v108
	v_lshlrev_b32_e32 v238, 16, v109
	v_and_b32_e32 v239, 0xffff0000, v109
	v_lshlrev_b32_e32 v240, 16, v110
	v_and_b32_e32 v241, 0xffff0000, v110
	v_lshlrev_b32_e32 v242, 16, v111
	v_and_b32_e32 v243, 0xffff0000, v111
	v_fmac_f32_e32 v246, v236, v236
	v_fmac_f32_e32 v246, v237, v237
	v_fmac_f32_e32 v246, v238, v238
	v_fmac_f32_e32 v246, v239, v239
	v_fmac_f32_e32 v246, v240, v240
	v_fmac_f32_e32 v246, v241, v241
	v_fmac_f32_e32 v246, v242, v242
	v_fmac_f32_e32 v246, v243, v243
	s_waitcnt vmcnt(10)
	v_lshlrev_b32_e32 v236, 16, v148
	v_and_b32_e32 v237, 0xffff0000, v148
	v_lshlrev_b32_e32 v238, 16, v149
	v_and_b32_e32 v239, 0xffff0000, v149
	v_lshlrev_b32_e32 v240, 16, v150
	v_and_b32_e32 v241, 0xffff0000, v150
	v_lshlrev_b32_e32 v242, 16, v151
	v_and_b32_e32 v243, 0xffff0000, v151
	v_pk_add_f32 v[236:237], v[76:77], v[236:237]
	v_pk_add_f32 v[238:239], v[78:79], v[238:239]
	v_pk_add_f32 v[240:241], v[72:73], v[240:241]
	v_pk_add_f32 v[242:243], v[74:75], v[242:243]
	v_cvt_pk_bf16_f32 v76, v236, v237
	v_cvt_pk_bf16_f32 v77, v238, v239
	v_cvt_pk_bf16_f32 v78, v240, v241
	v_cvt_pk_bf16_f32 v79, v242, v243
	v_lshlrev_b32_e32 v236, 16, v76
	v_and_b32_e32 v237, 0xffff0000, v76
	v_lshlrev_b32_e32 v238, 16, v77
	v_and_b32_e32 v239, 0xffff0000, v77
	v_lshlrev_b32_e32 v240, 16, v78
	v_and_b32_e32 v241, 0xffff0000, v78
	v_lshlrev_b32_e32 v242, 16, v79
	v_and_b32_e32 v243, 0xffff0000, v79
	v_fmac_f32_e32 v246, v236, v236
	v_fmac_f32_e32 v246, v237, v237
	v_fmac_f32_e32 v246, v238, v238
	v_fmac_f32_e32 v246, v239, v239
	v_fmac_f32_e32 v246, v240, v240
	v_fmac_f32_e32 v246, v241, v241
	v_fmac_f32_e32 v246, v242, v242
	v_fmac_f32_e32 v246, v243, v243
	s_waitcnt vmcnt(9)
	v_lshlrev_b32_e32 v236, 16, v152
	v_and_b32_e32 v237, 0xffff0000, v152
	v_lshlrev_b32_e32 v238, 16, v153
	v_and_b32_e32 v239, 0xffff0000, v153
	v_lshlrev_b32_e32 v240, 16, v154
	v_and_b32_e32 v241, 0xffff0000, v154
	v_lshlrev_b32_e32 v242, 16, v155
	v_and_b32_e32 v243, 0xffff0000, v155
	v_pk_add_f32 v[236:237], v[100:101], v[236:237]
	v_pk_add_f32 v[238:239], v[102:103], v[238:239]
	v_pk_add_f32 v[240:241], v[96:97], v[240:241]
	v_pk_add_f32 v[242:243], v[98:99], v[242:243]
	v_cvt_pk_bf16_f32 v100, v236, v237
	v_cvt_pk_bf16_f32 v101, v238, v239
	v_cvt_pk_bf16_f32 v102, v240, v241
	v_cvt_pk_bf16_f32 v103, v242, v243
	v_lshlrev_b32_e32 v236, 16, v100
	v_and_b32_e32 v237, 0xffff0000, v100
	v_lshlrev_b32_e32 v238, 16, v101
	v_and_b32_e32 v239, 0xffff0000, v101
	v_lshlrev_b32_e32 v240, 16, v102
	v_and_b32_e32 v241, 0xffff0000, v102
	v_lshlrev_b32_e32 v242, 16, v103
	v_and_b32_e32 v243, 0xffff0000, v103
	v_fmac_f32_e32 v247, v236, v236
	v_fmac_f32_e32 v247, v237, v237
	v_fmac_f32_e32 v247, v238, v238
	v_fmac_f32_e32 v247, v239, v239
	v_fmac_f32_e32 v247, v240, v240
	v_fmac_f32_e32 v247, v241, v241
	v_fmac_f32_e32 v247, v242, v242
	v_fmac_f32_e32 v247, v243, v243
	s_waitcnt vmcnt(8)
; __device__ __forceinline__ float bflo(unsigned w) { return __uint_as_float(w << 16); }
; __device__ __forceinline__ float bfhi(unsigned w) { return __uint_as_float(w & 0xffff0000u); }
;     __device__ __forceinline__ void operator()(const f32x4 (&acc)[2][2][4][2], const Unit& u, int wr, int wc, int fr_in, int fq_in) const {
;     ...
;                         for (int bj = 0; bj < 2; ++bj) { const u32x4 t = rb[m2][bj]; rv[m2][bj][0] = (f32x4){bflo(t.x), bfhi(t.x), bflo(t.y), bfhi(t.y)}; rv[m2][bj][1] = (f32x4){bflo(t.z), bfhi(t.z), bflo(t.w), bfhi(t.w)}; }
;                 }
;                 asm volatile("" ::: "memory");
; #pragma unroll
;                 for (int m2 = 0; m2 < 2; ++m2) { const int m = 2 * mh + m2; const size_t off = off0 + (size_t)(ai * HALF + m * 16) * u.ldc;
; #pragma unroll
;                     for (int bj = 0; bj < 2; ++bj) { const f32x4 v0 = acc[ai][bj][m][0] + rv[m2][bj][0], v1 = acc[ai][bj][m][1] + rv[m2][bj][1];
; template <bool OUT_F32, bool IN_BF16>
; __device__ __forceinline__ void phase_rmsnorm(const void* Xv, const float* gain, void* out) {
;     ...
;         for (int r = 0; r < RPT; ++r) { float sq = 0.f;
; #pragma unroll
;             for (int j = 0; j < 4; ++j) { if (IN_BF16) { const u32x4 q = t[r][j]; v[r][j][0] = (f32x4){bflo(q.x), bfhi(q.x), bflo(q.y), bfhi(q.y)}; v[r][j][1] = (f32x4){bflo(q.z), bfhi(q.z), bflo(q.w), bfhi(q.w)}; }
; #pragma unroll
;                 for (int h = 0; h < 2; ++h) { const f32x4 a = v[r][j][h]; sq += (a.x * a.x + a.y * a.y) + (a.z * a.z + a.w * a.w); } }
	v_lshlrev_b32_e32 v236, 16, v156
	v_and_b32_e32 v237, 0xffff0000, v156
	v_lshlrev_b32_e32 v238, 16, v157
	v_and_b32_e32 v239, 0xffff0000, v157
	v_lshlrev_b32_e32 v240, 16, v158
	v_and_b32_e32 v241, 0xffff0000, v158
	v_lshlrev_b32_e32 v242, 16, v159
	v_and_b32_e32 v243, 0xffff0000, v159
	v_pk_add_f32 v[236:237], v[68:69], v[236:237]
	v_pk_add_f32 v[238:239], v[70:71], v[238:239]
	v_pk_add_f32 v[240:241], v[64:65], v[240:241]
	v_pk_add_f32 v[242:243], v[66:67], v[242:243]
	v_cvt_pk_bf16_f32 v68, v236, v237
	v_cvt_pk_bf16_f32 v69, v238, v239
	v_cvt_pk_bf16_f32 v70, v240, v241
	v_cvt_pk_bf16_f32 v71, v242, v243
	v_lshlrev_b32_e32 v236, 16, v68
	v_and_b32_e32 v237, 0xffff0000, v68
	v_lshlrev_b32_e32 v238, 16, v69
	v_and_b32_e32 v239, 0xffff0000, v69
	v_lshlrev_b32_e32 v240, 16, v70
	v_and_b32_e32 v241, 0xffff0000, v70
	v_lshlrev_b32_e32 v242, 16, v71
	v_and_b32_e32 v243, 0xffff0000, v71
	v_fmac_f32_e32 v247, v236, v236
	v_fmac_f32_e32 v247, v237, v237
	v_fmac_f32_e32 v247, v238, v238
	v_fmac_f32_e32 v247, v239, v239
	v_fmac_f32_e32 v247, v240, v240
	v_fmac_f32_e32 v247, v241, v241
	v_fmac_f32_e32 v247, v242, v242
	v_fmac_f32_e32 v247, v243, v243
	s_waitcnt vmcnt(7)
	v_lshlrev_b32_e32 v236, 16, v192
	v_and_b32_e32 v237, 0xffff0000, v192
	v_lshlrev_b32_e32 v238, 16, v193
	v_and_b32_e32 v239, 0xffff0000, v193
	v_lshlrev_b32_e32 v240, 16, v194
	v_and_b32_e32 v241, 0xffff0000, v194
	v_lshlrev_b32_e32 v242, 16, v195
	v_and_b32_e32 v243, 0xffff0000, v195
	v_pk_add_f32 v[236:237], v[60:61], v[236:237]
	v_pk_add_f32 v[238:239], v[62:63], v[238:239]
	v_pk_add_f32 v[240:241], v[56:57], v[240:241]
	v_pk_add_f32 v[242:243], v[58:59], v[242:243]
	v_cvt_pk_bf16_f32 v60, v236, v237
	v_cvt_pk_bf16_f32 v61, v238, v239
	v_cvt_pk_bf16_f32 v62, v240, v241
	v_cvt_pk_bf16_f32 v63, v242, v243
	v_lshlrev_b32_e32 v236, 16, v60
	v_and_b32_e32 v237, 0xffff0000, v60
	v_lshlrev_b32_e32 v238, 16, v61
	v_and_b32_e32 v239, 0xffff0000, v61
	v_lshlrev_b32_e32 v240, 16, v62
	v_and_b32_e32 v241, 0xffff0000, v62
	v_lshlrev_b32_e32 v242, 16, v63
	v_and_b32_e32 v243, 0xffff0000, v63
	v_fmac_f32_e32 v248, v236, v236
	v_fmac_f32_e32 v248, v237, v237
	v_fmac_f32_e32 v248, v238, v238
	v_fmac_f32_e32 v248, v239, v239
	v_fmac_f32_e32 v248, v240, v240
	v_fmac_f32_e32 v248, v241, v241
	v_fmac_f32_e32 v248, v242, v242
	v_fmac_f32_e32 v248, v243, v243
	s_waitcnt vmcnt(6)
	v_lshlrev_b32_e32 v236, 16, v196
	v_and_b32_e32 v237, 0xffff0000, v196
	v_lshlrev_b32_e32 v238, 16, v197
	v_and_b32_e32 v239, 0xffff0000, v197
	v_lshlrev_b32_e32 v240, 16, v198
	v_and_b32_e32 v241, 0xffff0000, v198
	v_lshlrev_b32_e32 v242, 16, v199
	v_and_b32_e32 v243, 0xffff0000, v199
	v_pk_add_f32 v[236:237], v[28:29], v[236:237]
	v_pk_add_f32 v[238:239], v[30:31], v[238:239]
	v_pk_add_f32 v[240:241], v[24:25], v[240:241]
	v_pk_add_f32 v[242:243], v[26:27], v[242:243]
	v_cvt_pk_bf16_f32 v28, v236, v237
	v_cvt_pk_bf16_f32 v29, v238, v239
	v_cvt_pk_bf16_f32 v30, v240, v241
	v_cvt_pk_bf16_f32 v31, v242, v243
	v_lshlrev_b32_e32 v236, 16, v28
	v_and_b32_e32 v237, 0xffff0000, v28
	v_lshlrev_b32_e32 v238, 16, v29
	v_and_b32_e32 v239, 0xffff0000, v29
	v_lshlrev_b32_e32 v240, 16, v30
	v_and_b32_e32 v241, 0xffff0000, v30
	v_lshlrev_b32_e32 v242, 16, v31
	v_and_b32_e32 v243, 0xffff0000, v31
	v_fmac_f32_e32 v248, v236, v236
	v_fmac_f32_e32 v248, v237, v237
	v_fmac_f32_e32 v248, v238, v238
	v_fmac_f32_e32 v248, v239, v239
	v_fmac_f32_e32 v248, v240, v240
	v_fmac_f32_e32 v248, v241, v241
	v_fmac_f32_e32 v248, v242, v242
	v_fmac_f32_e32 v248, v243, v243
	s_waitcnt vmcnt(5)
	v_lshlrev_b32_e32 v236, 16, v200
	v_and_b32_e32 v237, 0xffff0000, v200
	v_lshlrev_b32_e32 v238, 16, v201
	v_and_b32_e32 v239, 0xffff0000, v201
	v_lshlrev_b32_e32 v240, 16, v202
	v_and_b32_e32 v241, 0xffff0000, v202
	v_lshlrev_b32_e32 v242, 16, v203
	v_and_b32_e32 v243, 0xffff0000, v203
	v_pk_add_f32 v[236:237], v[52:53], v[236:237]
	v_pk_add_f32 v[238:239], v[54:55], v[238:239]
	v_pk_add_f32 v[240:241], v[48:49], v[240:241]
	v_pk_add_f32 v[242:243], v[50:51], v[242:243]
	v_cvt_pk_bf16_f32 v52, v236, v237
	v_cvt_pk_bf16_f32 v53, v238, v239
	v_cvt_pk_bf16_f32 v54, v240, v241
	v_cvt_pk_bf16_f32 v55, v242, v243
	v_lshlrev_b32_e32 v236, 16, v52
	v_and_b32_e32 v237, 0xffff0000, v52
	v_lshlrev_b32_e32 v238, 16, v53
	v_and_b32_e32 v239, 0xffff0000, v53
	v_lshlrev_b32_e32 v240, 16, v54
	v_and_b32_e32 v241, 0xffff0000, v54
	v_lshlrev_b32_e32 v242, 16, v55
	v_and_b32_e32 v243, 0xffff0000, v55
	v_fmac_f32_e32 v249, v236, v236
	v_fmac_f32_e32 v249, v237, v237
	v_fmac_f32_e32 v249, v238, v238
	v_fmac_f32_e32 v249, v239, v239
	v_fmac_f32_e32 v249, v240, v240
	v_fmac_f32_e32 v249, v241, v241
	v_fmac_f32_e32 v249, v242, v242
	v_fmac_f32_e32 v249, v243, v243
	s_waitcnt vmcnt(4)
	v_lshlrev_b32_e32 v236, 16, v224
	v_and_b32_e32 v237, 0xffff0000, v224
	v_lshlrev_b32_e32 v238, 16, v225
	v_and_b32_e32 v239, 0xffff0000, v225
	v_lshlrev_b32_e32 v240, 16, v226
	v_and_b32_e32 v241, 0xffff0000, v226
	v_lshlrev_b32_e32 v242, 16, v227
	v_and_b32_e32 v243, 0xffff0000, v227
	v_pk_add_f32 v[236:237], v[20:21], v[236:237]
	v_pk_add_f32 v[238:239], v[22:23], v[238:239]
	v_pk_add_f32 v[240:241], v[16:17], v[240:241]
	v_pk_add_f32 v[242:243], v[18:19], v[242:243]
	v_cvt_pk_bf16_f32 v20, v236, v237
	v_cvt_pk_bf16_f32 v21, v238, v239
	v_cvt_pk_bf16_f32 v22, v240, v241
	v_cvt_pk_bf16_f32 v23, v242, v243
	v_lshlrev_b32_e32 v236, 16, v20
	v_and_b32_e32 v237, 0xffff0000, v20
	v_lshlrev_b32_e32 v238, 16, v21
	v_and_b32_e32 v239, 0xffff0000, v21
	v_lshlrev_b32_e32 v240, 16, v22
	v_and_b32_e32 v241, 0xffff0000, v22
	v_lshlrev_b32_e32 v242, 16, v23
	v_and_b32_e32 v243, 0xffff0000, v23
	v_fmac_f32_e32 v249, v236, v236
	v_fmac_f32_e32 v249, v237, v237
	v_fmac_f32_e32 v249, v238, v238
	v_fmac_f32_e32 v249, v239, v239
	v_fmac_f32_e32 v249, v240, v240
	v_fmac_f32_e32 v249, v241, v241
	v_fmac_f32_e32 v249, v242, v242
	v_fmac_f32_e32 v249, v243, v243
	s_waitcnt vmcnt(3)
; __device__ __forceinline__ float bflo(unsigned w) { return __uint_as_float(w << 16); }
; __device__ __forceinline__ float bfhi(unsigned w) { return __uint_as_float(w & 0xffff0000u); }
; __device__ __forceinline__ float wave_sum(float v) {
; #pragma unroll
;     for (int o = 1; o < 64; o <<= 1) v += __shfl_xor(v, o);
;     return v;
; template <bool OUT_F32, bool IN_BF16>
; __device__ __forceinline__ void phase_rmsnorm(const void* Xv, const float* gain, void* out) {
;     ...
;         for (int r = 0; r < RPT; ++r) { float sq = 0.f;
; #pragma unroll
;             for (int j = 0; j < 4; ++j) { if (IN_BF16) { const u32x4 q = t[r][j]; v[r][j][0] = (f32x4){bflo(q.x), bfhi(q.x), bflo(q.y), bfhi(q.y)}; v[r][j][1] = (f32x4){bflo(q.z), bfhi(q.z), bflo(q.w), bfhi(q.w)}; }
; #pragma unroll
;                 for (int h = 0; h < 2; ++h) { const f32x4 a = v[r][j][h]; sq += (a.x * a.x + a.y * a.y) + (a.z * a.z + a.w * a.w); } }
;             rs[r] = 1.0f / sqrtf(wave_sum(sq) * (1.0f / DM) + EPS); }
	v_lshlrev_b32_e32 v236, 16, v228
	v_and_b32_e32 v237, 0xffff0000, v228
	v_lshlrev_b32_e32 v238, 16, v229
	v_and_b32_e32 v239, 0xffff0000, v229
	v_lshlrev_b32_e32 v240, 16, v230
	v_and_b32_e32 v241, 0xffff0000, v230
	v_lshlrev_b32_e32 v242, 16, v231
	v_and_b32_e32 v243, 0xffff0000, v231
	v_pk_add_f32 v[236:237], v[44:45], v[236:237]
	v_pk_add_f32 v[238:239], v[46:47], v[238:239]
	v_pk_add_f32 v[240:241], v[40:41], v[240:241]
	v_pk_add_f32 v[242:243], v[42:43], v[242:243]
	v_cvt_pk_bf16_f32 v44, v236, v237
	v_cvt_pk_bf16_f32 v45, v238, v239
	v_cvt_pk_bf16_f32 v46, v240, v241
	v_cvt_pk_bf16_f32 v47, v242, v243
	v_lshlrev_b32_e32 v236, 16, v44
	v_and_b32_e32 v237, 0xffff0000, v44
	v_lshlrev_b32_e32 v238, 16, v45
	v_and_b32_e32 v239, 0xffff0000, v45
	v_lshlrev_b32_e32 v240, 16, v46
	v_and_b32_e32 v241, 0xffff0000, v46
	v_lshlrev_b32_e32 v242, 16, v47
	v_and_b32_e32 v243, 0xffff0000, v47
	v_fmac_f32_e32 v250, v236, v236
	v_fmac_f32_e32 v250, v237, v237
	v_fmac_f32_e32 v250, v238, v238
	v_fmac_f32_e32 v250, v239, v239
	v_fmac_f32_e32 v250, v240, v240
	v_fmac_f32_e32 v250, v241, v241
	v_fmac_f32_e32 v250, v242, v242
	v_fmac_f32_e32 v250, v243, v243
	s_waitcnt vmcnt(2)
	v_lshlrev_b32_e32 v236, 16, v232
	v_and_b32_e32 v237, 0xffff0000, v232
	v_lshlrev_b32_e32 v238, 16, v233
	v_and_b32_e32 v239, 0xffff0000, v233
	v_lshlrev_b32_e32 v240, 16, v234
	v_and_b32_e32 v241, 0xffff0000, v234
	v_lshlrev_b32_e32 v242, 16, v235
	v_and_b32_e32 v243, 0xffff0000, v235
	v_pk_add_f32 v[236:237], v[12:13], v[236:237]
	v_pk_add_f32 v[238:239], v[14:15], v[238:239]
	v_pk_add_f32 v[240:241], v[8:9], v[240:241]
	v_pk_add_f32 v[242:243], v[10:11], v[242:243]
	v_cvt_pk_bf16_f32 v12, v236, v237
	v_cvt_pk_bf16_f32 v13, v238, v239
	v_cvt_pk_bf16_f32 v14, v240, v241
	v_cvt_pk_bf16_f32 v15, v242, v243
	v_lshlrev_b32_e32 v236, 16, v12
	v_and_b32_e32 v237, 0xffff0000, v12
	v_lshlrev_b32_e32 v238, 16, v13
	v_and_b32_e32 v239, 0xffff0000, v13
	v_lshlrev_b32_e32 v240, 16, v14
	v_and_b32_e32 v241, 0xffff0000, v14
	v_lshlrev_b32_e32 v242, 16, v15
	v_and_b32_e32 v243, 0xffff0000, v15
	v_fmac_f32_e32 v250, v236, v236
	v_fmac_f32_e32 v250, v237, v237
	v_fmac_f32_e32 v250, v238, v238
	v_fmac_f32_e32 v250, v239, v239
	v_fmac_f32_e32 v250, v240, v240
	v_fmac_f32_e32 v250, v241, v241
	v_fmac_f32_e32 v250, v242, v242
	v_fmac_f32_e32 v250, v243, v243
	s_waitcnt vmcnt(1)
	v_lshlrev_b32_e32 v236, 16, v128
	v_and_b32_e32 v237, 0xffff0000, v128
	v_lshlrev_b32_e32 v238, 16, v129
	v_and_b32_e32 v239, 0xffff0000, v129
	v_lshlrev_b32_e32 v240, 16, v130
	v_and_b32_e32 v241, 0xffff0000, v130
	v_lshlrev_b32_e32 v242, 16, v131
	v_and_b32_e32 v243, 0xffff0000, v131
	v_pk_add_f32 v[236:237], v[36:37], v[236:237]
	v_pk_add_f32 v[238:239], v[38:39], v[238:239]
	v_pk_add_f32 v[240:241], v[32:33], v[240:241]
	v_pk_add_f32 v[242:243], v[34:35], v[242:243]
	v_cvt_pk_bf16_f32 v36, v236, v237
	v_cvt_pk_bf16_f32 v37, v238, v239
	v_cvt_pk_bf16_f32 v38, v240, v241
	v_cvt_pk_bf16_f32 v39, v242, v243
	v_lshlrev_b32_e32 v236, 16, v36
	v_and_b32_e32 v237, 0xffff0000, v36
	v_lshlrev_b32_e32 v238, 16, v37
	v_and_b32_e32 v239, 0xffff0000, v37
	v_lshlrev_b32_e32 v240, 16, v38
	v_and_b32_e32 v241, 0xffff0000, v38
	v_lshlrev_b32_e32 v242, 16, v39
	v_and_b32_e32 v243, 0xffff0000, v39
	v_fmac_f32_e32 v251, v236, v236
	v_fmac_f32_e32 v251, v237, v237
	v_fmac_f32_e32 v251, v238, v238
	v_fmac_f32_e32 v251, v239, v239
	v_fmac_f32_e32 v251, v240, v240
	v_fmac_f32_e32 v251, v241, v241
	v_fmac_f32_e32 v251, v242, v242
	v_fmac_f32_e32 v251, v243, v243
	s_waitcnt vmcnt(0)
	v_lshlrev_b32_e32 v236, 16, v132
	v_and_b32_e32 v237, 0xffff0000, v132
	v_lshlrev_b32_e32 v238, 16, v133
	v_and_b32_e32 v239, 0xffff0000, v133
	v_lshlrev_b32_e32 v240, 16, v134
	v_and_b32_e32 v241, 0xffff0000, v134
	v_lshlrev_b32_e32 v242, 16, v135
	v_and_b32_e32 v243, 0xffff0000, v135
	v_pk_add_f32 v[236:237], v[4:5], v[236:237]
	v_pk_add_f32 v[238:239], v[6:7], v[238:239]
	v_pk_add_f32 v[240:241], v[0:1], v[240:241]
	v_pk_add_f32 v[242:243], v[2:3], v[242:243]
	v_cvt_pk_bf16_f32 v4, v236, v237
	v_cvt_pk_bf16_f32 v5, v238, v239
	v_cvt_pk_bf16_f32 v6, v240, v241
	v_cvt_pk_bf16_f32 v7, v242, v243
	v_lshlrev_b32_e32 v236, 16, v4
	v_and_b32_e32 v237, 0xffff0000, v4
	v_lshlrev_b32_e32 v238, 16, v5
	v_and_b32_e32 v239, 0xffff0000, v5
	v_lshlrev_b32_e32 v240, 16, v6
	v_and_b32_e32 v241, 0xffff0000, v6
	v_lshlrev_b32_e32 v242, 16, v7
	v_and_b32_e32 v243, 0xffff0000, v7
	v_fmac_f32_e32 v251, v236, v236
	v_fmac_f32_e32 v251, v237, v237
	v_fmac_f32_e32 v251, v238, v238
	v_fmac_f32_e32 v251, v239, v239
	v_fmac_f32_e32 v251, v240, v240
	v_fmac_f32_e32 v251, v241, v241
	v_fmac_f32_e32 v251, v242, v242
	v_fmac_f32_e32 v251, v243, v243
	v_lshrrev_b32_e32 v40, 6, v185
	v_and_b32_e32 v41, 3, v40
	v_lshrrev_b32_e32 v40, 2, v40
	v_bfe_u32 v42, v185, 4, 2
	v_and_b32_e32 v43, 15, v185
	v_lshlrev_b32_e32 v24, 2, v41
	v_lshlrev_b32_e32 v41, 7, v41
	v_lshl_add_u32 v41, v42, 5, v41
	v_lshlrev_b32_e32 v40, 6, v40
	v_add_u32_e32 v40, v40, v43
	v_lshl_add_u32 v35, v40, 4, v24
	v_add_u32_e32 v35, 0x20000, v35
	v_lshlrev_b32_e32 v42, 4, v185
	v_add_u32_e32 v42, 0x20000, v42
	v_and_b32_e32 v3, 63, v185
	v_xor_b32_e32 v2, 16, v3
	v_lshlrev_b32_e32 v2, 2, v2
	v_xor_b32_e32 v3, 32, v3
	v_lshlrev_b32_e32 v3, 2, v3
	v_lshlrev_b32_e32 v43, 5, v185
	s_lshl_b32 s1, s0, 2
	v_add_u32_e32 v32, s1, v43
	v_mov_b32_e32 v33, 1
	ds_bpermute_b32 v120, v2, v244
	ds_bpermute_b32 v121, v2, v245
	ds_bpermute_b32 v122, v2, v246
	ds_bpermute_b32 v123, v2, v247
	ds_bpermute_b32 v112, v2, v248
	ds_bpermute_b32 v113, v2, v249
	ds_bpermute_b32 v114, v2, v250
	ds_bpermute_b32 v115, v2, v251
	s_waitcnt lgkmcnt(0)
	v_add_f32_e32 v244, v244, v120
	v_add_f32_e32 v245, v245, v121
	v_add_f32_e32 v246, v246, v122
	v_add_f32_e32 v247, v247, v123
	v_add_f32_e32 v248, v248, v112
	v_add_f32_e32 v249, v249, v113
	v_add_f32_e32 v250, v250, v114
	v_add_f32_e32 v251, v251, v115
	ds_bpermute_b32 v120, v3, v244
	ds_bpermute_b32 v121, v3, v245
	ds_bpermute_b32 v122, v3, v246
	ds_bpermute_b32 v123, v3, v247
	ds_bpermute_b32 v112, v3, v248
	ds_bpermute_b32 v113, v3, v249
	ds_bpermute_b32 v114, v3, v250
	ds_bpermute_b32 v115, v3, v251
	s_waitcnt lgkmcnt(0)
	v_add_f32_e32 v244, v244, v120
	v_add_f32_e32 v245, v245, v121
	v_add_f32_e32 v246, v246, v122
	v_add_f32_e32 v247, v247, v123
	v_add_f32_e32 v248, v248, v112
	v_add_f32_e32 v249, v249, v113
	v_add_f32_e32 v250, v250, v114
	v_add_f32_e32 v251, v251, v115
	v_and_b32_e32 v34, 48, v185
	v_cmp_eq_u32_e32 vcc, 0, v34
	s_and_saveexec_b64 s[64:65], vcc
	ds_write_b32 v35, v244 offset:0
	ds_write_b32 v35, v245 offset:256
	ds_write_b32 v35, v246 offset:512
	ds_write_b32 v35, v247 offset:768
	ds_write_b32 v35, v248 offset:2048
	ds_write_b32 v35, v249 offset:2304
	ds_write_b32 v35, v250 offset:2560
	ds_write_b32 v35, v251 offset:2816
	s_or_b64 exec, exec, s[64:65]
	s_waitcnt lgkmcnt(0)
	s_barrier
; __device__ __forceinline__ unsigned cvt_pk_bf16(float lo, float hi) { unsigned r; asm volatile("v_cvt_pk_bf16_f32 %0, %1, %2" : "=v"(r) : "v"(lo), "v"(hi)); return r; }
;     __device__ __forceinline__ void operator()(const f32x4 (&acc)[2][2][4][2], const Unit& u, int wr, int wc, int fr_in, int fq_in) const {
;     ...
;                 for (int m2 = 0; m2 < 2; ++m2) { const int m = 2 * mh + m2; const size_t off = off0 + (size_t)(ai * HALF + m * 16) * u.ldc;
; #pragma unroll
;                     for (int bj = 0; bj < 2; ++bj) { const f32x4 v0 = acc[ai][bj][m][0] + rv[m2][bj][0], v1 = acc[ai][bj][m][1] + rv[m2][bj][1];
;                         u32x4 w; w.x = cvt_pk_bf16(v0[0], v0[1]); w.y = cvt_pk_bf16(v0[2], v0[3]); w.z = cvt_pk_bf16(v1[0], v1[1]); w.w = cvt_pk_bf16(v1[2], v1[3]);
;                         *(u32x4*)(O + off + bj * HALF) = w; } }
; __device__ __forceinline__ unsigned xb_ld(unsigned* p)              { return __hip_atomic_load(p, __ATOMIC_RELAXED, __HIP_MEMORY_SCOPE_AGENT); }
; __device__ __forceinline__ unsigned xb_add(unsigned* p, unsigned v) { return __hip_atomic_fetch_add(p, v, __ATOMIC_RELAXED, __HIP_MEMORY_SCOPE_AGENT); }
; __device__ __forceinline__ unsigned xb_xcc_id() { return (unsigned)__builtin_amdgcn_s_getreg((3 << 11) | 20) & 0xFu; }
	v_cmp_gt_u32_e32 vcc, 0x100, v185
	s_and_saveexec_b64 s[64:65], vcc
	s_cbranch_execz .Lep_pub_done
	ds_read_b128 v[16:19], v42
	s_waitcnt lgkmcnt(0)
	v_add_f32_e32 v16, v16, v17
	v_add_f32_e32 v18, v18, v19
	v_add_f32_e32 v34, v16, v18
	global_store_dword v32, v34, s[38:39] sc0 sc1
	s_waitcnt vmcnt(0)
.Lep_pub_done:
	s_or_b64 exec, exec, s[64:65]
	s_barrier
	v_cmp_eq_u32_e32 vcc, 0, v185
	s_and_saveexec_b64 s[64:65], vcc
	global_atomic_add v183, v33, s[58:59]
	s_or_b64 exec, exec, s[64:65]
	global_load_dwordx4 v[88:91], v41, s[56:57]
	global_load_dwordx4 v[80:83], v41, s[56:57] offset:16
	global_load_dwordx4 v[72:75], v41, s[56:57] offset:512
	global_load_dwordx4 v[64:67], v41, s[56:57] offset:528
	s_mov_b32 s0, 0x10000
	s_mov_b32 s1, 0
	v_mov_b32_e32 v0, v174
	v_mov_b32_e32 v1, v175
	global_store_dwordx4 v[0:1], v[124:127], off
	global_store_dwordx4 v[0:1], v[92:95], off offset:256
	v_lshl_add_u64 v[0:1], v[0:1], 0, s[0:1]
	global_store_dwordx4 v[0:1], v[116:119], off
	global_store_dwordx4 v[0:1], v[84:87], off offset:256
	v_lshl_add_u64 v[0:1], v[0:1], 0, s[0:1]
	global_store_dwordx4 v[0:1], v[108:111], off
	global_store_dwordx4 v[0:1], v[76:79], off offset:256
	v_lshl_add_u64 v[0:1], v[0:1], 0, s[0:1]
	global_store_dwordx4 v[0:1], v[100:103], off
	global_store_dwordx4 v[0:1], v[68:71], off offset:256
	s_mov_b32 s0, 0x50000
	v_lshl_add_u64 v[0:1], v[0:1], 0, s[0:1]
	s_mov_b32 s0, 0x10000
	global_store_dwordx4 v[0:1], v[60:63], off
	global_store_dwordx4 v[0:1], v[28:31], off offset:256
	v_lshl_add_u64 v[0:1], v[0:1], 0, s[0:1]
	global_store_dwordx4 v[0:1], v[52:55], off
	global_store_dwordx4 v[0:1], v[20:23], off offset:256
	v_lshl_add_u64 v[0:1], v[0:1], 0, s[0:1]
	global_store_dwordx4 v[0:1], v[44:47], off
	global_store_dwordx4 v[0:1], v[12:15], off offset:256
	v_lshl_add_u64 v[0:1], v[0:1], 0, s[0:1]
	global_store_dwordx4 v[0:1], v[36:39], off
	global_store_dwordx4 v[0:1], v[4:7], off offset:256
	s_and_saveexec_b64 s[64:65], vcc
	s_cbranch_execz .Lep_wait_done
	s_mov_b32 s1, 0
.Lep_spin:
	global_load_dword v34, v183, s[58:59] sc1
	s_waitcnt vmcnt(0)
	v_cmp_gt_u32_e32 vcc, 8, v34
	s_cbranch_vccz .Lep_spin_done
	s_sleep 1
	s_add_i32 s1, s1, 1
	s_cmp_lt_u32 s1, 0x20000
	s_cbranch_scc1 .Lep_spin

; __device__ __forceinline__ unsigned pk2(float lo, float hi) { const f32x2 v = {lo, hi}; const hwbf16x2 b = __builtin_convertvector(v, hwbf16x2); return __builtin_bit_cast(unsigned, b); }
; template <bool OUT_F32, bool IN_BF16>
; __device__ __forceinline__ void phase_rmsnorm(const void* Xv, const float* gain, void* out) {
;     ...
;         for (int r = 0; r < RPT; ++r) { const int m = m0 + r * NGW; if (m >= NTOK) continue;
; #pragma unroll
;             for (int j = 0; j < 4; ++j) { const f32x4 y0 = v[r][j][0] * rs[r] * g[j][0], y1 = v[r][j][1] * rs[r] * g[j][1];
;                 if (OUT_F32) { float* o = (float*)out + (size_t)m * DM + 8 * lane + 512 * j; *(f32x4*)o = y0; *(f32x4*)(o + 4) = y1; }
;                 else { u32x4 w; w.x = pk2(y0.x, y0.y); w.y = pk2(y0.z, y0.w); w.z = pk2(y1.x, y1.y); w.w = pk2(y1.z, y1.w); *(u32x4*)((bf16_t*)out + (size_t)m * DM + 8 * lane + 512 * j) = w; } } }
.Lep_rs_done:
	s_or_b64 exec, exec, s[64:65]
	s_waitcnt lgkmcnt(0)
	s_barrier
	v_lshlrev_b32_e32 v2, 2, v40
	v_add_u32_e32 v2, 0x21000, v2
	ds_read_b32 v56, v2 offset:0
	ds_read_b32 v57, v2 offset:64
	ds_read_b32 v58, v2 offset:128
	ds_read_b32 v59, v2 offset:192
	ds_read_b32 v48, v2 offset:512
	ds_read_b32 v49, v2 offset:576
	ds_read_b32 v50, v2 offset:640
	ds_read_b32 v51, v2 offset:704
	s_mov_b32 s64, 0x4000000
	s_mov_b32 s65, 0
	v_lshl_add_u64 v[0:1], v[174:175], 0, s[64:65]
	s_mov_b32 s64, 0x10000
	s_waitcnt vmcnt(0) lgkmcnt(0)
	v_lshlrev_b32_e32 v120, 16, v124
	v_and_b32_e32 v121, 0xffff0000, v124
	v_lshlrev_b32_e32 v122, 16, v125
	v_and_b32_e32 v123, 0xffff0000, v125
	v_lshlrev_b32_e32 v112, 16, v126
	v_and_b32_e32 v113, 0xffff0000, v126
	v_lshlrev_b32_e32 v114, 16, v127
	v_and_b32_e32 v115, 0xffff0000, v127
	v_mul_f32_e32 v120, v120, v56
	v_mul_f32_e32 v121, v121, v56
	v_mul_f32_e32 v122, v122, v56
	v_mul_f32_e32 v123, v123, v56
	v_mul_f32_e32 v112, v112, v56
	v_mul_f32_e32 v113, v113, v56
	v_mul_f32_e32 v114, v114, v56
	v_mul_f32_e32 v115, v115, v56
	v_pk_mul_f32 v[120:121], v[120:121], v[88:89]
	v_pk_mul_f32 v[122:123], v[122:123], v[90:91]
	v_pk_mul_f32 v[112:113], v[112:113], v[80:81]
	v_pk_mul_f32 v[114:115], v[114:115], v[82:83]
	v_cvt_pk_bf16_f32 v8, v120, v121
	v_cvt_pk_bf16_f32 v9, v122, v123
	v_cvt_pk_bf16_f32 v10, v112, v113
	v_cvt_pk_bf16_f32 v11, v114, v115
	global_store_dwordx4 v[0:1], v[8:11], off
	v_lshlrev_b32_e32 v120, 16, v92
	v_and_b32_e32 v121, 0xffff0000, v92
	v_lshlrev_b32_e32 v122, 16, v93
	v_and_b32_e32 v123, 0xffff0000, v93
	v_lshlrev_b32_e32 v112, 16, v94
	v_and_b32_e32 v113, 0xffff0000, v94
	v_lshlrev_b32_e32 v114, 16, v95
	v_and_b32_e32 v115, 0xffff0000, v95
	v_mul_f32_e32 v120, v120, v56
	v_mul_f32_e32 v121, v121, v56
	v_mul_f32_e32 v122, v122, v56
	v_mul_f32_e32 v123, v123, v56
	v_mul_f32_e32 v112, v112, v56
	v_mul_f32_e32 v113, v113, v56
	v_mul_f32_e32 v114, v114, v56
	v_mul_f32_e32 v115, v115, v56
	v_pk_mul_f32 v[120:121], v[120:121], v[72:73]
	v_pk_mul_f32 v[122:123], v[122:123], v[74:75]
	v_pk_mul_f32 v[112:113], v[112:113], v[64:65]
	v_pk_mul_f32 v[114:115], v[114:115], v[66:67]
	v_cvt_pk_bf16_f32 v8, v120, v121
	v_cvt_pk_bf16_f32 v9, v122, v123
	v_cvt_pk_bf16_f32 v10, v112, v113
	v_cvt_pk_bf16_f32 v11, v114, v115
	global_store_dwordx4 v[0:1], v[8:11], off offset:256
	v_lshl_add_u64 v[0:1], v[0:1], 0, s[64:65]
	v_lshlrev_b32_e32 v120, 16, v116
	v_and_b32_e32 v121, 0xffff0000, v116
	v_lshlrev_b32_e32 v122, 16, v117
	v_and_b32_e32 v123, 0xffff0000, v117
	v_lshlrev_b32_e32 v112, 16, v118
	v_and_b32_e32 v113, 0xffff0000, v118
	v_lshlrev_b32_e32 v114, 16, v119
	v_and_b32_e32 v115, 0xffff0000, v119
	v_mul_f32_e32 v120, v120, v57
	v_mul_f32_e32 v121, v121, v57
	v_mul_f32_e32 v122, v122, v57
	v_mul_f32_e32 v123, v123, v57
	v_mul_f32_e32 v112, v112, v57
	v_mul_f32_e32 v113, v113, v57
	v_mul_f32_e32 v114, v114, v57
	v_mul_f32_e32 v115, v115, v57
	v_pk_mul_f32 v[120:121], v[120:121], v[88:89]
	v_pk_mul_f32 v[122:123], v[122:123], v[90:91]
	v_pk_mul_f32 v[112:113], v[112:113], v[80:81]
	v_pk_mul_f32 v[114:115], v[114:115], v[82:83]
	v_cvt_pk_bf16_f32 v8, v120, v121
	v_cvt_pk_bf16_f32 v9, v122, v123
	v_cvt_pk_bf16_f32 v10, v112, v113
	v_cvt_pk_bf16_f32 v11, v114, v115
	global_store_dwordx4 v[0:1], v[8:11], off
	v_lshlrev_b32_e32 v120, 16, v84
	v_and_b32_e32 v121, 0xffff0000, v84
	v_lshlrev_b32_e32 v122, 16, v85
	v_and_b32_e32 v123, 0xffff0000, v85
	v_lshlrev_b32_e32 v112, 16, v86
	v_and_b32_e32 v113, 0xffff0000, v86
	v_lshlrev_b32_e32 v114, 16, v87
	v_and_b32_e32 v115, 0xffff0000, v87
	v_mul_f32_e32 v120, v120, v57
	v_mul_f32_e32 v121, v121, v57
	v_mul_f32_e32 v122, v122, v57
	v_mul_f32_e32 v123, v123, v57
	v_mul_f32_e32 v112, v112, v57
	v_mul_f32_e32 v113, v113, v57
	v_mul_f32_e32 v114, v114, v57
	v_mul_f32_e32 v115, v115, v57
	v_pk_mul_f32 v[120:121], v[120:121], v[72:73]
	v_pk_mul_f32 v[122:123], v[122:123], v[74:75]
	v_pk_mul_f32 v[112:113], v[112:113], v[64:65]
	v_pk_mul_f32 v[114:115], v[114:115], v[66:67]
	v_cvt_pk_bf16_f32 v8, v120, v121
	v_cvt_pk_bf16_f32 v9, v122, v123
	v_cvt_pk_bf16_f32 v10, v112, v113
	v_cvt_pk_bf16_f32 v11, v114, v115
	global_store_dwordx4 v[0:1], v[8:11], off offset:256
	v_lshl_add_u64 v[0:1], v[0:1], 0, s[64:65]
	v_lshlrev_b32_e32 v120, 16, v108
	v_and_b32_e32 v121, 0xffff0000, v108
	v_lshlrev_b32_e32 v122, 16, v109
	v_and_b32_e32 v123, 0xffff0000, v109
	v_lshlrev_b32_e32 v112, 16, v110
	v_and_b32_e32 v113, 0xffff0000, v110
	v_lshlrev_b32_e32 v114, 16, v111
	v_and_b32_e32 v115, 0xffff0000, v111
	v_mul_f32_e32 v120, v120, v58
	v_mul_f32_e32 v121, v121, v58
	v_mul_f32_e32 v122, v122, v58
	v_mul_f32_e32 v123, v123, v58
	v_mul_f32_e32 v112, v112, v58
	v_mul_f32_e32 v113, v113, v58
	v_mul_f32_e32 v114, v114, v58
	v_mul_f32_e32 v115, v115, v58
	v_pk_mul_f32 v[120:121], v[120:121], v[88:89]
	v_pk_mul_f32 v[122:123], v[122:123], v[90:91]
	v_pk_mul_f32 v[112:113], v[112:113], v[80:81]
	v_pk_mul_f32 v[114:115], v[114:115], v[82:83]
	v_cvt_pk_bf16_f32 v8, v120, v121
	v_cvt_pk_bf16_f32 v9, v122, v123
	v_cvt_pk_bf16_f32 v10, v112, v113
	v_cvt_pk_bf16_f32 v11, v114, v115
	global_store_dwordx4 v[0:1], v[8:11], off
	v_lshlrev_b32_e32 v120, 16, v76
	v_and_b32_e32 v121, 0xffff0000, v76
	v_lshlrev_b32_e32 v122, 16, v77
	v_and_b32_e32 v123, 0xffff0000, v77
	v_lshlrev_b32_e32 v112, 16, v78
	v_and_b32_e32 v113, 0xffff0000, v78
	v_lshlrev_b32_e32 v114, 16, v79
	v_and_b32_e32 v115, 0xffff0000, v79
	v_mul_f32_e32 v120, v120, v58
	v_mul_f32_e32 v121, v121, v58
	v_mul_f32_e32 v122, v122, v58
	v_mul_f32_e32 v123, v123, v58
	v_mul_f32_e32 v112, v112, v58
	v_mul_f32_e32 v113, v113, v58
	v_mul_f32_e32 v114, v114, v58
; __device__ __forceinline__ unsigned pk2(float lo, float hi) { const f32x2 v = {lo, hi}; const hwbf16x2 b = __builtin_convertvector(v, hwbf16x2); return __builtin_bit_cast(unsigned, b); }
; template <bool OUT_F32, bool IN_BF16>
; __device__ __forceinline__ void phase_rmsnorm(const void* Xv, const float* gain, void* out) {
;     ...
;         for (int r = 0; r < RPT; ++r) { const int m = m0 + r * NGW; if (m >= NTOK) continue;
; #pragma unroll
;             for (int j = 0; j < 4; ++j) { const f32x4 y0 = v[r][j][0] * rs[r] * g[j][0], y1 = v[r][j][1] * rs[r] * g[j][1];
;                 if (OUT_F32) { float* o = (float*)out + (size_t)m * DM + 8 * lane + 512 * j; *(f32x4*)o = y0; *(f32x4*)(o + 4) = y1; }
;                 else { u32x4 w; w.x = pk2(y0.x, y0.y); w.y = pk2(y0.z, y0.w); w.z = pk2(y1.x, y1.y); w.w = pk2(y1.z, y1.w); *(u32x4*)((bf16_t*)out + (size_t)m * DM + 8 * lane + 512 * j) = w; } } }
	v_mul_f32_e32 v115, v115, v58
	v_pk_mul_f32 v[120:121], v[120:121], v[72:73]
	v_pk_mul_f32 v[122:123], v[122:123], v[74:75]
	v_pk_mul_f32 v[112:113], v[112:113], v[64:65]
	v_pk_mul_f32 v[114:115], v[114:115], v[66:67]
	v_cvt_pk_bf16_f32 v8, v120, v121
	v_cvt_pk_bf16_f32 v9, v122, v123
	v_cvt_pk_bf16_f32 v10, v112, v113
	v_cvt_pk_bf16_f32 v11, v114, v115
	global_store_dwordx4 v[0:1], v[8:11], off offset:256
	v_lshl_add_u64 v[0:1], v[0:1], 0, s[64:65]
	v_lshlrev_b32_e32 v120, 16, v100
	v_and_b32_e32 v121, 0xffff0000, v100
	v_lshlrev_b32_e32 v122, 16, v101
	v_and_b32_e32 v123, 0xffff0000, v101
	v_lshlrev_b32_e32 v112, 16, v102
	v_and_b32_e32 v113, 0xffff0000, v102
	v_lshlrev_b32_e32 v114, 16, v103
	v_and_b32_e32 v115, 0xffff0000, v103
	v_mul_f32_e32 v120, v120, v59
	v_mul_f32_e32 v121, v121, v59
	v_mul_f32_e32 v122, v122, v59
	v_mul_f32_e32 v123, v123, v59
	v_mul_f32_e32 v112, v112, v59
	v_mul_f32_e32 v113, v113, v59
	v_mul_f32_e32 v114, v114, v59
	v_mul_f32_e32 v115, v115, v59
	v_pk_mul_f32 v[120:121], v[120:121], v[88:89]
	v_pk_mul_f32 v[122:123], v[122:123], v[90:91]
	v_pk_mul_f32 v[112:113], v[112:113], v[80:81]
	v_pk_mul_f32 v[114:115], v[114:115], v[82:83]
	v_cvt_pk_bf16_f32 v8, v120, v121
	v_cvt_pk_bf16_f32 v9, v122, v123
	v_cvt_pk_bf16_f32 v10, v112, v113
	v_cvt_pk_bf16_f32 v11, v114, v115
	global_store_dwordx4 v[0:1], v[8:11], off
	v_lshlrev_b32_e32 v120, 16, v68
	v_and_b32_e32 v121, 0xffff0000, v68
	v_lshlrev_b32_e32 v122, 16, v69
	v_and_b32_e32 v123, 0xffff0000, v69
	v_lshlrev_b32_e32 v112, 16, v70
	v_and_b32_e32 v113, 0xffff0000, v70
	v_lshlrev_b32_e32 v114, 16, v71
	v_and_b32_e32 v115, 0xffff0000, v71
	v_mul_f32_e32 v120, v120, v59
	v_mul_f32_e32 v121, v121, v59
	v_mul_f32_e32 v122, v122, v59
	v_mul_f32_e32 v123, v123, v59
	v_mul_f32_e32 v112, v112, v59
	v_mul_f32_e32 v113, v113, v59
	v_mul_f32_e32 v114, v114, v59
	v_mul_f32_e32 v115, v115, v59
	v_pk_mul_f32 v[120:121], v[120:121], v[72:73]
	v_pk_mul_f32 v[122:123], v[122:123], v[74:75]
	v_pk_mul_f32 v[112:113], v[112:113], v[64:65]
	v_pk_mul_f32 v[114:115], v[114:115], v[66:67]
	v_cvt_pk_bf16_f32 v8, v120, v121
	v_cvt_pk_bf16_f32 v9, v122, v123
	v_cvt_pk_bf16_f32 v10, v112, v113
	v_cvt_pk_bf16_f32 v11, v114, v115
	global_store_dwordx4 v[0:1], v[8:11], off offset:256
	s_mov_b32 s64, 0x50000
	v_lshl_add_u64 v[0:1], v[0:1], 0, s[64:65]
	s_mov_b32 s64, 0x10000
	v_lshlrev_b32_e32 v120, 16, v60
	v_and_b32_e32 v121, 0xffff0000, v60
	v_lshlrev_b32_e32 v122, 16, v61
	v_and_b32_e32 v123, 0xffff0000, v61
	v_lshlrev_b32_e32 v112, 16, v62
	v_and_b32_e32 v113, 0xffff0000, v62
	v_lshlrev_b32_e32 v114, 16, v63
	v_and_b32_e32 v115, 0xffff0000, v63
	v_mul_f32_e32 v120, v120, v48
	v_mul_f32_e32 v121, v121, v48
	v_mul_f32_e32 v122, v122, v48
	v_mul_f32_e32 v123, v123, v48
	v_mul_f32_e32 v112, v112, v48
	v_mul_f32_e32 v113, v113, v48
	v_mul_f32_e32 v114, v114, v48
	v_mul_f32_e32 v115, v115, v48
	v_pk_mul_f32 v[120:121], v[120:121], v[88:89]
	v_pk_mul_f32 v[122:123], v[122:123], v[90:91]
	v_pk_mul_f32 v[112:113], v[112:113], v[80:81]
	v_pk_mul_f32 v[114:115], v[114:115], v[82:83]
	v_cvt_pk_bf16_f32 v8, v120, v121
	v_cvt_pk_bf16_f32 v9, v122, v123
	v_cvt_pk_bf16_f32 v10, v112, v113
	v_cvt_pk_bf16_f32 v11, v114, v115
	global_store_dwordx4 v[0:1], v[8:11], off
	v_lshlrev_b32_e32 v120, 16, v28
	v_and_b32_e32 v121, 0xffff0000, v28
	v_lshlrev_b32_e32 v122, 16, v29
	v_and_b32_e32 v123, 0xffff0000, v29
	v_lshlrev_b32_e32 v112, 16, v30
	v_and_b32_e32 v113, 0xffff0000, v30
	v_lshlrev_b32_e32 v114, 16, v31
	v_and_b32_e32 v115, 0xffff0000, v31
	v_mul_f32_e32 v120, v120, v48
	v_mul_f32_e32 v121, v121, v48
	v_mul_f32_e32 v122, v122, v48
	v_mul_f32_e32 v123, v123, v48
	v_mul_f32_e32 v112, v112, v48
	v_mul_f32_e32 v113, v113, v48
	v_mul_f32_e32 v114, v114, v48
	v_mul_f32_e32 v115, v115, v48
	v_pk_mul_f32 v[120:121], v[120:121], v[72:73]
	v_pk_mul_f32 v[122:123], v[122:123], v[74:75]
	v_pk_mul_f32 v[112:113], v[112:113], v[64:65]
	v_pk_mul_f32 v[114:115], v[114:115], v[66:67]
	v_cvt_pk_bf16_f32 v8, v120, v121
	v_cvt_pk_bf16_f32 v9, v122, v123
	v_cvt_pk_bf16_f32 v10, v112, v113
	v_cvt_pk_bf16_f32 v11, v114, v115
	global_store_dwordx4 v[0:1], v[8:11], off offset:256
	v_lshl_add_u64 v[0:1], v[0:1], 0, s[64:65]
	v_lshlrev_b32_e32 v120, 16, v52
	v_and_b32_e32 v121, 0xffff0000, v52
	v_lshlrev_b32_e32 v122, 16, v53
	v_and_b32_e32 v123, 0xffff0000, v53
	v_lshlrev_b32_e32 v112, 16, v54
	v_and_b32_e32 v113, 0xffff0000, v54
	v_lshlrev_b32_e32 v114, 16, v55
	v_and_b32_e32 v115, 0xffff0000, v55
	v_mul_f32_e32 v120, v120, v49
	v_mul_f32_e32 v121, v121, v49
	v_mul_f32_e32 v122, v122, v49
	v_mul_f32_e32 v123, v123, v49
	v_mul_f32_e32 v112, v112, v49
	v_mul_f32_e32 v113, v113, v49
	v_mul_f32_e32 v114, v114, v49
	v_mul_f32_e32 v115, v115, v49
	v_pk_mul_f32 v[120:121], v[120:121], v[88:89]
	v_pk_mul_f32 v[122:123], v[122:123], v[90:91]
	v_pk_mul_f32 v[112:113], v[112:113], v[80:81]
	v_pk_mul_f32 v[114:115], v[114:115], v[82:83]
	v_cvt_pk_bf16_f32 v8, v120, v121
; __device__ __forceinline__ unsigned pk2(float lo, float hi) { const f32x2 v = {lo, hi}; const hwbf16x2 b = __builtin_convertvector(v, hwbf16x2); return __builtin_bit_cast(unsigned, b); }
; template <bool OUT_F32, bool IN_BF16>
; __device__ __forceinline__ void phase_rmsnorm(const void* Xv, const float* gain, void* out) {
;     ...
;         for (int r = 0; r < RPT; ++r) { const int m = m0 + r * NGW; if (m >= NTOK) continue;
; #pragma unroll
;             for (int j = 0; j < 4; ++j) { const f32x4 y0 = v[r][j][0] * rs[r] * g[j][0], y1 = v[r][j][1] * rs[r] * g[j][1];
;                 if (OUT_F32) { float* o = (float*)out + (size_t)m * DM + 8 * lane + 512 * j; *(f32x4*)o = y0; *(f32x4*)(o + 4) = y1; }
;                 else { u32x4 w; w.x = pk2(y0.x, y0.y); w.y = pk2(y0.z, y0.w); w.z = pk2(y1.x, y1.y); w.w = pk2(y1.z, y1.w); *(u32x4*)((bf16_t*)out + (size_t)m * DM + 8 * lane + 512 * j) = w; } } }
	v_cvt_pk_bf16_f32 v9, v122, v123
	v_cvt_pk_bf16_f32 v10, v112, v113
	v_cvt_pk_bf16_f32 v11, v114, v115
	global_store_dwordx4 v[0:1], v[8:11], off
	v_lshlrev_b32_e32 v120, 16, v20
	v_and_b32_e32 v121, 0xffff0000, v20
	v_lshlrev_b32_e32 v122, 16, v21
	v_and_b32_e32 v123, 0xffff0000, v21
	v_lshlrev_b32_e32 v112, 16, v22
	v_and_b32_e32 v113, 0xffff0000, v22
	v_lshlrev_b32_e32 v114, 16, v23
	v_and_b32_e32 v115, 0xffff0000, v23
	v_mul_f32_e32 v120, v120, v49
	v_mul_f32_e32 v121, v121, v49
	v_mul_f32_e32 v122, v122, v49
	v_mul_f32_e32 v123, v123, v49
	v_mul_f32_e32 v112, v112, v49
	v_mul_f32_e32 v113, v113, v49
	v_mul_f32_e32 v114, v114, v49
	v_mul_f32_e32 v115, v115, v49
	v_pk_mul_f32 v[120:121], v[120:121], v[72:73]
	v_pk_mul_f32 v[122:123], v[122:123], v[74:75]
	v_pk_mul_f32 v[112:113], v[112:113], v[64:65]
	v_pk_mul_f32 v[114:115], v[114:115], v[66:67]
	v_cvt_pk_bf16_f32 v8, v120, v121
	v_cvt_pk_bf16_f32 v9, v122, v123
	v_cvt_pk_bf16_f32 v10, v112, v113
	v_cvt_pk_bf16_f32 v11, v114, v115
	global_store_dwordx4 v[0:1], v[8:11], off offset:256
	v_lshl_add_u64 v[0:1], v[0:1], 0, s[64:65]
	v_lshlrev_b32_e32 v120, 16, v44
	v_and_b32_e32 v121, 0xffff0000, v44
	v_lshlrev_b32_e32 v122, 16, v45
	v_and_b32_e32 v123, 0xffff0000, v45
	v_lshlrev_b32_e32 v112, 16, v46
	v_and_b32_e32 v113, 0xffff0000, v46
	v_lshlrev_b32_e32 v114, 16, v47
	v_and_b32_e32 v115, 0xffff0000, v47
	v_mul_f32_e32 v120, v120, v50
	v_mul_f32_e32 v121, v121, v50
	v_mul_f32_e32 v122, v122, v50
	v_mul_f32_e32 v123, v123, v50
	v_mul_f32_e32 v112, v112, v50
	v_mul_f32_e32 v113, v113, v50
	v_mul_f32_e32 v114, v114, v50
	v_mul_f32_e32 v115, v115, v50
	v_pk_mul_f32 v[120:121], v[120:121], v[88:89]
	v_pk_mul_f32 v[122:123], v[122:123], v[90:91]
	v_pk_mul_f32 v[112:113], v[112:113], v[80:81]
	v_pk_mul_f32 v[114:115], v[114:115], v[82:83]
	v_cvt_pk_bf16_f32 v8, v120, v121
	v_cvt_pk_bf16_f32 v9, v122, v123
	v_cvt_pk_bf16_f32 v10, v112, v113
	v_cvt_pk_bf16_f32 v11, v114, v115
	global_store_dwordx4 v[0:1], v[8:11], off
	v_lshlrev_b32_e32 v120, 16, v12
	v_and_b32_e32 v121, 0xffff0000, v12
	v_lshlrev_b32_e32 v122, 16, v13
	v_and_b32_e32 v123, 0xffff0000, v13
	v_lshlrev_b32_e32 v112, 16, v14
	v_and_b32_e32 v113, 0xffff0000, v14
	v_lshlrev_b32_e32 v114, 16, v15
	v_and_b32_e32 v115, 0xffff0000, v15
	v_mul_f32_e32 v120, v120, v50
	v_mul_f32_e32 v121, v121, v50
	v_mul_f32_e32 v122, v122, v50
	v_mul_f32_e32 v123, v123, v50
	v_mul_f32_e32 v112, v112, v50
	v_mul_f32_e32 v113, v113, v50
	v_mul_f32_e32 v114, v114, v50
	v_mul_f32_e32 v115, v115, v50
	v_pk_mul_f32 v[120:121], v[120:121], v[72:73]
	v_pk_mul_f32 v[122:123], v[122:123], v[74:75]
	v_pk_mul_f32 v[112:113], v[112:113], v[64:65]
	v_pk_mul_f32 v[114:115], v[114:115], v[66:67]
	v_cvt_pk_bf16_f32 v8, v120, v121
	v_cvt_pk_bf16_f32 v9, v122, v123
	v_cvt_pk_bf16_f32 v10, v112, v113
	v_cvt_pk_bf16_f32 v11, v114, v115
	global_store_dwordx4 v[0:1], v[8:11], off offset:256
	v_lshl_add_u64 v[0:1], v[0:1], 0, s[64:65]
	v_lshlrev_b32_e32 v120, 16, v36
	v_and_b32_e32 v121, 0xffff0000, v36
	v_lshlrev_b32_e32 v122, 16, v37
	v_and_b32_e32 v123, 0xffff0000, v37
	v_lshlrev_b32_e32 v112, 16, v38
	v_and_b32_e32 v113, 0xffff0000, v38
	v_lshlrev_b32_e32 v114, 16, v39
	v_and_b32_e32 v115, 0xffff0000, v39
	v_mul_f32_e32 v120, v120, v51
	v_mul_f32_e32 v121, v121, v51
	v_mul_f32_e32 v122, v122, v51
	v_mul_f32_e32 v123, v123, v51
	v_mul_f32_e32 v112, v112, v51
	v_mul_f32_e32 v113, v113, v51
	v_mul_f32_e32 v114, v114, v51
	v_mul_f32_e32 v115, v115, v51
	v_pk_mul_f32 v[120:121], v[120:121], v[88:89]
	v_pk_mul_f32 v[122:123], v[122:123], v[90:91]
	v_pk_mul_f32 v[112:113], v[112:113], v[80:81]
	v_pk_mul_f32 v[114:115], v[114:115], v[82:83]
	v_cvt_pk_bf16_f32 v8, v120, v121
	v_cvt_pk_bf16_f32 v9, v122, v123
	v_cvt_pk_bf16_f32 v10, v112, v113
	v_cvt_pk_bf16_f32 v11, v114, v115
	global_store_dwordx4 v[0:1], v[8:11], off
	v_lshlrev_b32_e32 v120, 16, v4
	v_and_b32_e32 v121, 0xffff0000, v4
	v_lshlrev_b32_e32 v122, 16, v5
	v_and_b32_e32 v123, 0xffff0000, v5
	v_lshlrev_b32_e32 v112, 16, v6
	v_and_b32_e32 v113, 0xffff0000, v6
	v_lshlrev_b32_e32 v114, 16, v7
	v_and_b32_e32 v115, 0xffff0000, v7
	v_mul_f32_e32 v120, v120, v51
	v_mul_f32_e32 v121, v121, v51
	v_mul_f32_e32 v122, v122, v51
	v_mul_f32_e32 v123, v123, v51
	v_mul_f32_e32 v112, v112, v51
	v_mul_f32_e32 v113, v113, v51
	v_mul_f32_e32 v114, v114, v51
	v_mul_f32_e32 v115, v115, v51
	v_pk_mul_f32 v[120:121], v[120:121], v[72:73]
	v_pk_mul_f32 v[122:123], v[122:123], v[74:75]
	v_pk_mul_f32 v[112:113], v[112:113], v[64:65]
	v_pk_mul_f32 v[114:115], v[114:115], v[66:67]
	v_cvt_pk_bf16_f32 v8, v120, v121
	v_cvt_pk_bf16_f32 v9, v122, v123
	v_cvt_pk_bf16_f32 v10, v112, v113
	v_cvt_pk_bf16_f32 v11, v114, v115
	global_store_dwordx4 v[0:1], v[8:11], off offset:256
	s_movk_i32 s56, 0x1f8
	s_movk_i32 s57, 0x1fff
	s_mov_b32 s58, 0x2c000
	s_mov_b32 s59, 0x84000
	s_mov_b32 s64, 0xb0000
	s_mov_b32 s65, 0xdc000
	s_mov_b64 vcc, s[100:101]
	s_cbranch_vccnz .LBB0_282
	s_branch .Lln_ret
